# attention loop v4: software-pipelined over the iteration boundary, 4 fragment buffers, per-tile max chain replaced by a partial-row-sum overflow screen (exact max only on the rare path), row-sum halve
# speedup vs baseline: 1.0175x; 1.0175x over previous
.Latt_entry:
	s_mov_b32 s98, s47
	s_mov_b32 s99, s46
	v_mov_b32_e32 v209, 1.0
	v_mov_b32_e32 v26, 1.0
	s_not_b64 exec, s[10:11]
	v_mov_b32_e32 v206, 0
	s_mov_b64 exec, -1
	v_exp_f32_e32 v96, v96
	v_exp_f32_e32 v97, v97
	v_exp_f32_e32 v98, v98
	v_exp_f32_e32 v99, v99
	v_exp_f32_e32 v100, v100
	v_add_f32_e32 v17, 0, v96
	v_exp_f32_e32 v101, v101
	v_add_f32_e32 v17, v97, v17
	v_exp_f32_e32 v102, v102
	v_add_f32_e32 v17, v98, v17
	v_exp_f32_e32 v103, v103
	v_add_f32_e32 v17, v99, v17
	v_exp_f32_e32 v104, v104
	v_add_f32_e32 v17, v100, v17
	v_exp_f32_e32 v105, v105
	v_add_f32_e32 v17, v101, v17
	v_exp_f32_e32 v106, v106
	v_add_f32_e32 v17, v102, v17
	v_exp_f32_e32 v107, v107
	v_add_f32_e32 v17, v103, v17
	v_exp_f32_e32 v108, v108
	v_add_f32_e32 v17, v104, v17
	v_exp_f32_e32 v109, v109
	v_add_f32_e32 v17, v105, v17
	v_exp_f32_e32 v110, v110
	v_add_f32_e32 v17, v106, v17
	v_exp_f32_e32 v111, v111
	v_add_f32_e32 v17, v107, v17
	v_exp_f32_e32 v112, v112
	v_add_f32_e32 v17, v108, v17
	s_add_i32 s12, s71, 1
	s_cmp_lg_u32 s71, 4
	s_cselect_b32 s12, s12, 0
	s_mul_i32 s100, s12, 0x5c00
	v_add3_u32 v31, s100, v205, v187
	ds_read_b128 v[210:213], v31
	ds_read_b128 v[214:217], v31 offset:16
	ds_read_b128 v[218:221], v31 offset:6656
	ds_read_b128 v[222:225], v31 offset:6672
	s_add_i32 s13, s12, 1
	s_cmp_lg_u32 s12, 4
	s_cselect_b32 s55, s13, 0
	s_add_i32 s13, s55, 1
	s_cmp_lg_u32 s55, 4
	s_cselect_b32 s13, s13, 0
	s_add_i32 s87, s13, 1
	s_cmp_lg_u32 s13, 4
	s_cselect_b32 s87, s87, 0
	s_mul_i32 s48, s71, 0x5c00
	s_mul_i32 s101, s55, 0x5c00
	s_mul_i32 s70, s13, 0x5c00
	s_mulk_i32 s87, 0x5c00
	v_add_u32_e32 v242, s48, v208
	ds_read_b128 v[226:229], v31 offset:64
	ds_read_b128 v[230:233], v31 offset:80
	s_cmpk_gt_u32 s54, 0x80
	s_cbranch_scc1 .Latt_s_d1x
	s_add_u32 s84, s98, 0xffffd000
	s_addc_u32 s85, s99, -1
	s_add_u32 s88, s52, 0xffffe000
	s_addc_u32 s89, s53, -1
	s_add_i32 m0, s70, s3
	s_and_b64 s[48:49], s[66:67], exec
	global_load_lds_dwordx4 v184, s[84:85]
	s_cselect_b32 s49, s85, s89
	s_cselect_b32 s48, s84, s88
	s_add_i32 m0, s70, s14
	s_and_b64 vcc, exec, s[8:9]
	global_load_lds_dwordx4 v190, s[48:49]
	s_cbranch_vccnz .Latt_s_d1x
	s_add_i32 m0, s70, s15
	s_nop 0
	global_load_lds_dwordx4 v188, s[88:89]
.Latt_s_d1x:
	s_cmpk_gt_u32 s54, 0x7f
	s_cbranch_scc1 .Latt_s_d2x
	s_add_i32 m0, s87, s3
	s_and_b64 s[48:49], s[66:67], exec
	global_load_lds_dwordx4 v184, s[98:99]
	s_cselect_b32 s49, s99, s53
	s_cselect_b32 s48, s98, s52
	s_add_i32 m0, s87, s14
	s_and_b64 vcc, exec, s[8:9]
	global_load_lds_dwordx4 v190, s[48:49]
	s_cbranch_vccnz .Latt_s_d2x
	s_add_i32 m0, s87, s15
	s_nop 0
	global_load_lds_dwordx4 v188, s[52:53]
.Latt_s_d2x:
.Latt_slot1:
	s_waitcnt lgkmcnt(4)
	v_mfma_f32_32x32x64_f8f6f4 v[144:159], v[210:217], v[160:167], v[80:95]
	ds_read_b128 v[234:237], v31 offset:6720
	ds_read_b128 v[238:241], v31 offset:6736
	v_exp_f32_e32 v113, v113
	v_add_f32_e32 v17, v109, v17
	v_exp_f32_e32 v114, v114
	v_add_f32_e32 v17, v110, v17
	v_exp_f32_e32 v115, v115
	v_add_f32_e32 v17, v111, v17
	v_exp_f32_e32 v116, v116
	v_add_f32_e32 v17, v112, v17
	s_waitcnt lgkmcnt(4)
	v_mfma_f32_32x32x64_f8f6f4 v[128:143], v[218:225], v[160:167], v[80:95]
	ds_read_b128 v[210:213], v31 offset:128
	ds_read_b128 v[214:217], v31 offset:144
	v_exp_f32_e32 v117, v117
	v_add_f32_e32 v17, v113, v17
	v_exp_f32_e32 v118, v118
	v_add_f32_e32 v17, v114, v17
	v_exp_f32_e32 v119, v119
	v_add_f32_e32 v17, v115, v17
	v_exp_f32_e32 v120, v120
	s_waitcnt lgkmcnt(4)
	v_mfma_f32_32x32x64_f8f6f4 v[144:159], v[226:233], v[168:175], v[144:159]
	ds_read_b128 v[218:221], v31 offset:6784
	ds_read_b128 v[222:225], v31 offset:6800
	v_add_f32_e32 v17, v116, v17
	v_exp_f32_e32 v121, v121
	v_add_f32_e32 v17, v117, v17
	v_exp_f32_e32 v122, v122
	v_add_f32_e32 v17, v118, v17
	v_exp_f32_e32 v123, v123
	v_add_f32_e32 v17, v119, v17
	v_exp_f32_e32 v124, v124
	s_waitcnt lgkmcnt(4)
	v_mfma_f32_32x32x64_f8f6f4 v[128:143], v[234:241], v[168:175], v[128:143]
	ds_read_b128 v[226:229], v242 offset:13312
	ds_read_b128 v[230:233], v242 offset:13344
	v_add_f32_e32 v17, v120, v17
	v_exp_f32_e32 v125, v125
	v_add_f32_e32 v17, v121, v17
	v_exp_f32_e32 v126, v126
	v_add_f32_e32 v17, v122, v17
	v_exp_f32_e32 v127, v127
	v_add_f32_e32 v17, v123, v17
	v_add_f32_e32 v17, v124, v17
	s_waitcnt lgkmcnt(4)
	v_mfma_f32_32x32x64_f8f6f4 v[144:159], v[210:217], v[176:183], v[144:159]
	ds_read_b128 v[234:237], v242 offset:15872
	ds_read_b128 v[238:241], v242 offset:15904
	v_add_f32_e32 v17, v125, v17
	v_add_f32_e32 v17, v126, v17
	v_add_f32_e32 v28, v127, v17
	v_cmp_lt_f32_e32 vcc, 0x43d80000, v28
	s_cbranch_vccnz .Latt_slow_A
.Latt_A_cont:
	v_fma_f32 v206, v206, v209, v28
	v_cvt_pk_fp8_f32 v18, v96, v97
	v_cvt_pk_fp8_f32 v22, v112, v113
	v_cvt_pk_fp8_f32 v19, v100, v101
	v_cvt_pk_fp8_f32 v23, v116, v117
	v_cvt_pk_fp8_f32 v20, v104, v105
	v_add_u32_e32 v31, s101, v192
	s_waitcnt lgkmcnt(4)
	v_mfma_f32_32x32x64_f8f6f4 v[128:143], v[218:225], v[176:183], v[128:143]
	ds_read_b128 v[210:213], v242 offset:18432
	ds_read_b128 v[214:217], v242 offset:18464
	v_cvt_pk_fp8_f32 v24, v120, v121
	v_cvt_pk_fp8_f32 v21, v108, v109
	v_cvt_pk_fp8_f32 v25, v124, v125
	v_cvt_pk_fp8_f32 v18, v98, v99 op_sel:[0,0,1]
	v_cvt_pk_fp8_f32 v22, v114, v115 op_sel:[0,0,1]
	v_cvt_pk_fp8_f32 v19, v102, v103 op_sel:[0,0,1]
	v_cvt_pk_fp8_f32 v23, v118, v119 op_sel:[0,0,1]
	v_cvt_pk_fp8_f32 v20, v106, v107 op_sel:[0,0,1]
	v_cvt_pk_fp8_f32 v24, v122, v123 op_sel:[0,0,1]
	v_cvt_pk_fp8_f32 v21, v110, v111 op_sel:[0,0,1]
	v_cvt_pk_fp8_f32 v25, v126, v127 op_sel:[0,0,1]
	v_cmp_gt_f32_e32 vcc, 1.0, v209
	s_cbranch_vccnz .Latt_resc_A
.Latt_rescA_cont:
	s_waitcnt lgkmcnt(4)
	v_mfma_f32_32x32x64_f8f6f4 v[32:47], v[18:25], v[226:233], v[32:47]
	ds_read_b128 v[218:221], v242 offset:20992
	ds_read_b128 v[222:225], v242 offset:21024
	v_exp_f32_e32 v144, v144
	v_exp_f32_e32 v145, v145
	v_exp_f32_e32 v146, v146
	v_exp_f32_e32 v147, v147
	v_exp_f32_e32 v148, v148
	v_add_f32_e32 v17, 0, v144
	v_exp_f32_e32 v149, v149
	s_waitcnt lgkmcnt(4)
	v_mfma_f32_32x32x64_f8f6f4 v[48:63], v[18:25], v[234:241], v[48:63]
	ds_read_b128 v[226:229], v31
	ds_read_b128 v[230:233], v31 offset:16
	v_add_f32_e32 v17, v145, v17
	v_exp_f32_e32 v150, v150
	v_add_f32_e32 v17, v146, v17
	v_exp_f32_e32 v151, v151
	v_add_f32_e32 v17, v147, v17
	v_exp_f32_e32 v152, v152
	v_add_f32_e32 v17, v148, v17
	v_exp_f32_e32 v153, v153
	s_waitcnt lgkmcnt(4)
	v_mfma_f32_32x32x64_f8f6f4 v[64:79], v[18:25], v[210:217], v[64:79]
	ds_read_b128 v[234:237], v31 offset:6656
	ds_read_b128 v[238:241], v31 offset:6672
	v_add3_u32 v242, s100, v207, v193
	v_add_f32_e32 v17, v149, v17
	v_exp_f32_e32 v154, v154
	v_add_f32_e32 v17, v150, v17
	v_exp_f32_e32 v155, v155
	v_add_f32_e32 v17, v151, v17
	v_exp_f32_e32 v156, v156
	v_add_f32_e32 v17, v152, v17
	v_exp_f32_e32 v157, v157
	s_waitcnt lgkmcnt(4)
	v_mfma_f32_32x32x64_f8f6f4 v[0:15], v[18:25], v[218:225], v[0:15]
	ds_read_b128 v[210:213], v31 offset:64
	ds_read_b128 v[214:217], v31 offset:80
	v_add_f32_e32 v17, v153, v17
	v_exp_f32_e32 v158, v158
	v_add_f32_e32 v17, v154, v17
	v_exp_f32_e32 v159, v159
	v_add_f32_e32 v17, v155, v17
	v_exp_f32_e32 v128, v128
	v_add_f32_e32 v17, v156, v17
	s_waitcnt lgkmcnt(4)
	v_mfma_f32_32x32x64_f8f6f4 v[96:111], v[226:233], v[160:167], v[80:95]
	ds_read_b128 v[218:221], v31 offset:6720
	ds_read_b128 v[222:225], v31 offset:6736
	v_exp_f32_e32 v129, v129
	v_add_f32_e32 v17, v157, v17
	v_exp_f32_e32 v130, v130
	v_add_f32_e32 v17, v158, v17
	v_exp_f32_e32 v131, v131
	v_add_f32_e32 v17, v159, v17
	v_exp_f32_e32 v132, v132
	v_add_f32_e32 v17, v128, v17
	s_waitcnt lgkmcnt(4)
	v_mfma_f32_32x32x64_f8f6f4 v[112:127], v[234:241], v[160:167], v[80:95]
	ds_read_b128 v[226:229], v31 offset:128
	ds_read_b128 v[230:233], v31 offset:144
	v_exp_f32_e32 v133, v133
	v_add_f32_e32 v17, v129, v17
	v_exp_f32_e32 v134, v134
	v_add_f32_e32 v17, v130, v17
	v_exp_f32_e32 v135, v135
	v_add_f32_e32 v17, v131, v17
	v_exp_f32_e32 v136, v136
	s_waitcnt lgkmcnt(4)
	v_mfma_f32_32x32x64_f8f6f4 v[96:111], v[210:217], v[168:175], v[96:111]
	ds_read_b128 v[234:237], v31 offset:6784
	ds_read_b128 v[238:241], v31 offset:6800
	v_add_f32_e32 v17, v132, v17
	v_exp_f32_e32 v137, v137
	v_add_f32_e32 v17, v133, v17
	v_exp_f32_e32 v138, v138
	v_add_f32_e32 v17, v134, v17
	v_exp_f32_e32 v139, v139
	v_add_f32_e32 v17, v135, v17
	v_exp_f32_e32 v140, v140
	s_waitcnt lgkmcnt(4)
	v_mfma_f32_32x32x64_f8f6f4 v[112:127], v[218:225], v[168:175], v[112:127]
	ds_read_b128 v[210:213], v242 offset:13312
	ds_read_b128 v[214:217], v242 offset:13344
	v_add_f32_e32 v17, v136, v17
	v_exp_f32_e32 v141, v141
	v_add_f32_e32 v17, v137, v17
	v_exp_f32_e32 v142, v142
	v_add_f32_e32 v17, v138, v17
	v_exp_f32_e32 v143, v143
	v_add_f32_e32 v17, v139, v17
	v_add_f32_e32 v17, v140, v17
	s_waitcnt lgkmcnt(4)
	v_mfma_f32_32x32x64_f8f6f4 v[96:111], v[226:233], v[176:183], v[96:111]
	ds_read_b128 v[218:221], v242 offset:15872
	ds_read_b128 v[222:225], v242 offset:15904
	v_add_f32_e32 v17, v141, v17
	v_add_f32_e32 v17, v142, v17
	v_add_f32_e32 v28, v143, v17
	v_cmp_lt_f32_e32 vcc, 0x43d80000, v28
	s_cbranch_vccnz .Latt_slow_B
.Latt_B_cont:
	v_fma_f32 v206, v206, v26, v28
	v_cvt_pk_fp8_f32 v18, v144, v145
	v_cvt_pk_fp8_f32 v22, v128, v129
	v_cvt_pk_fp8_f32 v19, v148, v149
	v_cvt_pk_fp8_f32 v23, v132, v133
	v_cvt_pk_fp8_f32 v20, v152, v153
	s_waitcnt lgkmcnt(4)
	v_mfma_f32_32x32x64_f8f6f4 v[112:127], v[234:241], v[176:183], v[112:127]
	ds_read_b128 v[226:229], v242 offset:18432
	ds_read_b128 v[230:233], v242 offset:18464
	v_cvt_pk_fp8_f32 v24, v136, v137
	v_cvt_pk_fp8_f32 v21, v156, v157
	v_cvt_pk_fp8_f32 v25, v140, v141
	v_cvt_pk_fp8_f32 v18, v146, v147 op_sel:[0,0,1]
	v_cvt_pk_fp8_f32 v22, v130, v131 op_sel:[0,0,1]
	v_cvt_pk_fp8_f32 v19, v150, v151 op_sel:[0,0,1]
	v_cvt_pk_fp8_f32 v23, v134, v135 op_sel:[0,0,1]
	v_cvt_pk_fp8_f32 v20, v154, v155 op_sel:[0,0,1]
	v_cvt_pk_fp8_f32 v24, v138, v139 op_sel:[0,0,1]
	v_cvt_pk_fp8_f32 v21, v158, v159 op_sel:[0,0,1]
	v_cvt_pk_fp8_f32 v25, v142, v143 op_sel:[0,0,1]
	v_cmp_gt_f32_e32 vcc, 1.0, v26
	s_cbranch_vccnz .Latt_resc_B
.Latt_rescB_cont:
	s_waitcnt lgkmcnt(4)
	v_mfma_f32_32x32x64_f8f6f4 v[32:47], v[18:25], v[210:217], v[32:47]
	ds_read_b128 v[234:237], v242 offset:20992
	ds_read_b128 v[238:241], v242 offset:21024
	v_exp_f32_e32 v96, v96
	v_exp_f32_e32 v97, v97
	v_exp_f32_e32 v98, v98
	v_exp_f32_e32 v99, v99
	v_exp_f32_e32 v100, v100
	v_add_f32_e32 v17, 0, v96
	v_exp_f32_e32 v101, v101
	s_waitcnt lgkmcnt(4)
	v_mfma_f32_32x32x64_f8f6f4 v[48:63], v[18:25], v[218:225], v[48:63]
	v_add_f32_e32 v17, v97, v17
	v_exp_f32_e32 v102, v102
	v_add_f32_e32 v17, v98, v17
	v_exp_f32_e32 v103, v103
	v_add_f32_e32 v17, v99, v17
	v_exp_f32_e32 v104, v104
	v_add_f32_e32 v17, v100, v17
	v_exp_f32_e32 v105, v105
	s_waitcnt vmcnt(0) lgkmcnt(0)
	s_barrier
	s_add_i32 s54, s54, 2
	s_add_u32 s52, s52, 0x4000
	s_addc_u32 s53, s53, 0
	s_add_u32 s98, s98, 0x6000
	s_addc_u32 s99, s99, 0
	s_mov_b32 s71, s55
	s_cmpk_gt_u32 s54, 0x82
	s_cbranch_scc1 .Latt_exit
	v_mfma_f32_32x32x64_f8f6f4 v[64:79], v[18:25], v[226:233], v[64:79]
	s_add_i32 s12, s71, 1
	s_cmp_lg_u32 s71, 4
	s_cselect_b32 s12, s12, 0
	s_mul_i32 s100, s12, 0x5c00
	v_add3_u32 v31, s100, v205, v187
	ds_read_b128 v[210:213], v31
	ds_read_b128 v[214:217], v31 offset:16
	ds_read_b128 v[218:221], v31 offset:6656
	ds_read_b128 v[222:225], v31 offset:6672
	s_add_i32 s13, s12, 1
	s_cmp_lg_u32 s12, 4
	s_cselect_b32 s55, s13, 0
	s_add_i32 s13, s55, 1
	s_cmp_lg_u32 s55, 4
	s_cselect_b32 s13, s13, 0
	s_add_i32 s87, s13, 1
	s_cmp_lg_u32 s13, 4
	s_cselect_b32 s87, s87, 0
	s_mul_i32 s48, s71, 0x5c00
	s_mul_i32 s101, s55, 0x5c00
	s_mul_i32 s70, s13, 0x5c00
	s_mulk_i32 s87, 0x5c00
	v_add_u32_e32 v242, s48, v208
	v_add_f32_e32 v17, v101, v17
	v_exp_f32_e32 v106, v106
	v_add_f32_e32 v17, v102, v17
	v_exp_f32_e32 v107, v107
	v_add_f32_e32 v17, v103, v17
	v_exp_f32_e32 v108, v108
	v_add_f32_e32 v17, v104, v17
	v_exp_f32_e32 v109, v109
	v_mfma_f32_32x32x64_f8f6f4 v[0:15], v[18:25], v[234:241], v[0:15]
	ds_read_b128 v[226:229], v31 offset:64
	ds_read_b128 v[230:233], v31 offset:80
	v_add_f32_e32 v17, v105, v17
	v_exp_f32_e32 v110, v110
	v_add_f32_e32 v17, v106, v17
	v_exp_f32_e32 v111, v111
	v_add_f32_e32 v17, v107, v17
	v_exp_f32_e32 v112, v112
	v_add_f32_e32 v17, v108, v17
	s_cmpk_gt_u32 s54, 0x80
	s_cbranch_scc1 .Latt_l_d1x
	s_add_u32 s84, s98, 0xffffd000
	s_addc_u32 s85, s99, -1
	s_add_u32 s88, s52, 0xffffe000
	s_addc_u32 s89, s53, -1
	s_add_i32 m0, s70, s3
	s_and_b64 s[48:49], s[66:67], exec
	global_load_lds_dwordx4 v184, s[84:85]
	s_cselect_b32 s49, s85, s89
	s_cselect_b32 s48, s84, s88
	s_add_i32 m0, s70, s14
	s_and_b64 vcc, exec, s[8:9]
	global_load_lds_dwordx4 v190, s[48:49]
	s_cbranch_vccnz .Latt_l_d1x
	s_add_i32 m0, s70, s15
	s_nop 0
	global_load_lds_dwordx4 v188, s[88:89]

.Latt_l_d2x:
	s_branch .Latt_slot1
.Latt_exit:
	v_mfma_f32_32x32x64_f8f6f4 v[64:79], v[18:25], v[226:233], v[64:79]
	v_mfma_f32_32x32x64_f8f6f4 v[0:15], v[18:25], v[234:241], v[0:15]
	v_mov_b32_e32 v27, v206
	s_nop 1
	v_permlane32_swap_b32_e32 v206, v27
	v_add_f32_e32 v206, v206, v27
	s_branch .LBB0_879
.Latt_slow_A:
	v_max_f32_e32 v17, v96, v97
	v_max3_f32 v17, v17, v98, v99
	v_max3_f32 v17, v17, v100, v101
	v_max3_f32 v17, v17, v102, v103
	v_max3_f32 v17, v17, v104, v105
	v_max3_f32 v17, v17, v106, v107
	v_max3_f32 v17, v17, v108, v109
	v_max3_f32 v17, v17, v110, v111
	v_max3_f32 v17, v17, v112, v113
	v_max3_f32 v17, v17, v114, v115
	v_max3_f32 v17, v17, v116, v117
	v_max3_f32 v17, v17, v118, v119
	v_max3_f32 v17, v17, v120, v121
	v_max3_f32 v17, v17, v122, v123
	v_max3_f32 v17, v17, v124, v125
	v_max3_f32 v17, v17, v126, v127
	v_mov_b32_e32 v27, v17
	s_nop 1
	v_permlane32_swap_b32_e32 v17, v27
	v_max_f32_e32 v17, v17, v27
	v_log_f32_e32 v17, v17
	s_nop 0
	v_cmp_lt_f32_e32 vcc, s81, v17
	s_cbranch_vccz .Latt_A_cont
	v_add_f32_e32 v17, -4.0, v17
	v_max_f32_e32 v27, 0, v17
	v_sub_f32_e32 v16, v16, v27
	v_exp_f32_e64 v209, -v27
	s_nop 0
	v_mul_f32_e32 v96, v96, v209
	v_mul_f32_e32 v97, v97, v209
	v_mul_f32_e32 v98, v98, v209
	v_mul_f32_e32 v99, v99, v209
	v_mul_f32_e32 v100, v100, v209
	v_mul_f32_e32 v101, v101, v209
	v_mul_f32_e32 v102, v102, v209
	v_mul_f32_e32 v103, v103, v209
	v_mul_f32_e32 v104, v104, v209
	v_mul_f32_e32 v105, v105, v209
	v_mul_f32_e32 v106, v106, v209
	v_mul_f32_e32 v107, v107, v209
	v_mul_f32_e32 v108, v108, v209
	v_mul_f32_e32 v109, v109, v209
	v_mul_f32_e32 v110, v110, v209
	v_mul_f32_e32 v111, v111, v209
	v_mul_f32_e32 v112, v112, v209
	v_mul_f32_e32 v113, v113, v209
	v_mul_f32_e32 v114, v114, v209
	v_mul_f32_e32 v115, v115, v209
	v_mul_f32_e32 v116, v116, v209
	v_mul_f32_e32 v117, v117, v209
	v_mul_f32_e32 v118, v118, v209
	v_mul_f32_e32 v119, v119, v209
	v_mul_f32_e32 v120, v120, v209
	v_mul_f32_e32 v121, v121, v209
	v_mul_f32_e32 v122, v122, v209
	v_mul_f32_e32 v123, v123, v209
	v_mul_f32_e32 v124, v124, v209
	v_mul_f32_e32 v125, v125, v209
	v_mul_f32_e32 v126, v126, v209
	v_mul_f32_e32 v127, v127, v209
	v_mul_f32_e32 v28, v28, v209
	s_nop 15
	s_nop 7
	v_sub_f32_e32 v144, v144, v27
	v_sub_f32_e32 v145, v145, v27
	v_sub_f32_e32 v146, v146, v27
	v_sub_f32_e32 v147, v147, v27
	v_sub_f32_e32 v148, v148, v27
	v_sub_f32_e32 v149, v149, v27
	v_sub_f32_e32 v150, v150, v27
	v_sub_f32_e32 v151, v151, v27
	v_sub_f32_e32 v152, v152, v27
	v_sub_f32_e32 v153, v153, v27
	v_sub_f32_e32 v154, v154, v27
	v_sub_f32_e32 v155, v155, v27
	v_sub_f32_e32 v156, v156, v27
	v_sub_f32_e32 v157, v157, v27
	v_sub_f32_e32 v158, v158, v27
	v_sub_f32_e32 v159, v159, v27
	v_sub_f32_e32 v128, v128, v27
	v_sub_f32_e32 v129, v129, v27
	v_sub_f32_e32 v130, v130, v27
	v_sub_f32_e32 v131, v131, v27
	v_sub_f32_e32 v132, v132, v27
	v_sub_f32_e32 v133, v133, v27
	v_sub_f32_e32 v134, v134, v27
	v_sub_f32_e32 v135, v135, v27
	v_sub_f32_e32 v136, v136, v27
	v_sub_f32_e32 v137, v137, v27
	v_sub_f32_e32 v138, v138, v27
	v_sub_f32_e32 v139, v139, v27
	v_sub_f32_e32 v140, v140, v27
	v_sub_f32_e32 v141, v141, v27
	v_sub_f32_e32 v142, v142, v27
	v_sub_f32_e32 v143, v143, v27
	v_mov_b32_e32 v80, v16
	v_mov_b32_e32 v81, v16
	v_mov_b32_e32 v82, v16
	v_mov_b32_e32 v83, v16
	v_mov_b32_e32 v84, v16
	v_mov_b32_e32 v85, v16
	v_mov_b32_e32 v86, v16
	v_mov_b32_e32 v87, v16
	v_mov_b32_e32 v88, v16
	v_mov_b32_e32 v89, v16
	v_mov_b32_e32 v90, v16
	v_mov_b32_e32 v91, v16
	v_mov_b32_e32 v92, v16
	v_mov_b32_e32 v93, v16
	v_mov_b32_e32 v94, v16
	v_mov_b32_e32 v95, v16
	s_branch .Latt_A_cont
.Latt_slow_B:
	v_max_f32_e32 v17, v144, v145
	v_max3_f32 v17, v17, v146, v147
	v_max3_f32 v17, v17, v148, v149
	v_max3_f32 v17, v17, v150, v151
	v_max3_f32 v17, v17, v152, v153
	v_max3_f32 v17, v17, v154, v155
	v_max3_f32 v17, v17, v156, v157
	v_max3_f32 v17, v17, v158, v159
	v_max3_f32 v17, v17, v128, v129
	v_max3_f32 v17, v17, v130, v131
	v_max3_f32 v17, v17, v132, v133
	v_max3_f32 v17, v17, v134, v135
	v_max3_f32 v17, v17, v136, v137
	v_max3_f32 v17, v17, v138, v139
	v_max3_f32 v17, v17, v140, v141
	v_max3_f32 v17, v17, v142, v143
	v_mov_b32_e32 v27, v17
	s_nop 1
	v_permlane32_swap_b32_e32 v17, v27
	v_max_f32_e32 v17, v17, v27
	v_log_f32_e32 v17, v17
	s_nop 0
	v_cmp_lt_f32_e32 vcc, s81, v17
	s_cbranch_vccz .Latt_B_cont
	v_add_f32_e32 v17, -4.0, v17
	v_max_f32_e32 v27, 0, v17
	v_sub_f32_e32 v16, v16, v27
	v_exp_f32_e64 v26, -v27
	s_nop 0
	v_mul_f32_e32 v144, v144, v26
	v_mul_f32_e32 v145, v145, v26
	v_mul_f32_e32 v146, v146, v26
	v_mul_f32_e32 v147, v147, v26
	v_mul_f32_e32 v148, v148, v26
	v_mul_f32_e32 v149, v149, v26
	v_mul_f32_e32 v150, v150, v26
	v_mul_f32_e32 v151, v151, v26
	v_mul_f32_e32 v152, v152, v26
	v_mul_f32_e32 v153, v153, v26
	v_mul_f32_e32 v154, v154, v26
	v_mul_f32_e32 v155, v155, v26
	v_mul_f32_e32 v156, v156, v26
	v_mul_f32_e32 v157, v157, v26
	v_mul_f32_e32 v158, v158, v26
	v_mul_f32_e32 v159, v159, v26
	v_mul_f32_e32 v128, v128, v26
	v_mul_f32_e32 v129, v129, v26
	v_mul_f32_e32 v130, v130, v26
	v_mul_f32_e32 v131, v131, v26
	v_mul_f32_e32 v132, v132, v26
	v_mul_f32_e32 v133, v133, v26
	v_mul_f32_e32 v134, v134, v26
	v_mul_f32_e32 v135, v135, v26
	v_mul_f32_e32 v136, v136, v26
	v_mul_f32_e32 v137, v137, v26
	v_mul_f32_e32 v138, v138, v26
	v_mul_f32_e32 v139, v139, v26
	v_mul_f32_e32 v140, v140, v26
	v_mul_f32_e32 v141, v141, v26
	v_mul_f32_e32 v142, v142, v26
	v_mul_f32_e32 v143, v143, v26
	v_mul_f32_e32 v28, v28, v26
	s_nop 15
	s_nop 7
	v_sub_f32_e32 v96, v96, v27
	v_sub_f32_e32 v97, v97, v27
	v_sub_f32_e32 v98, v98, v27
	v_sub_f32_e32 v99, v99, v27
	v_sub_f32_e32 v100, v100, v27
	v_sub_f32_e32 v101, v101, v27
	v_sub_f32_e32 v102, v102, v27
	v_sub_f32_e32 v103, v103, v27
	v_sub_f32_e32 v104, v104, v27
	v_sub_f32_e32 v105, v105, v27
	v_sub_f32_e32 v106, v106, v27
	v_sub_f32_e32 v107, v107, v27
	v_sub_f32_e32 v108, v108, v27
	v_sub_f32_e32 v109, v109, v27
	v_sub_f32_e32 v110, v110, v27
	v_sub_f32_e32 v111, v111, v27
	v_sub_f32_e32 v112, v112, v27
	v_sub_f32_e32 v113, v113, v27
	v_sub_f32_e32 v114, v114, v27
	v_sub_f32_e32 v115, v115, v27
	v_sub_f32_e32 v116, v116, v27
	v_sub_f32_e32 v117, v117, v27
	v_sub_f32_e32 v118, v118, v27
	v_sub_f32_e32 v119, v119, v27
	v_sub_f32_e32 v120, v120, v27
	v_sub_f32_e32 v121, v121, v27
	v_sub_f32_e32 v122, v122, v27
	v_sub_f32_e32 v123, v123, v27
	v_sub_f32_e32 v124, v124, v27
	v_sub_f32_e32 v125, v125, v27
	v_sub_f32_e32 v126, v126, v27
	v_sub_f32_e32 v127, v127, v27
	v_mov_b32_e32 v80, v16
	v_mov_b32_e32 v81, v16
	v_mov_b32_e32 v82, v16
	v_mov_b32_e32 v83, v16
	v_mov_b32_e32 v84, v16
	v_mov_b32_e32 v85, v16
	v_mov_b32_e32 v86, v16
	v_mov_b32_e32 v87, v16
	v_mov_b32_e32 v88, v16
	v_mov_b32_e32 v89, v16
	v_mov_b32_e32 v90, v16
	v_mov_b32_e32 v91, v16
	v_mov_b32_e32 v92, v16
	v_mov_b32_e32 v93, v16
	v_mov_b32_e32 v94, v16
	v_mov_b32_e32 v95, v16
	s_branch .Latt_B_cont
.Latt_resc_A:
	s_and_saveexec_b64 s[12:13], s[10:11]
	ds_write_b32 v195, v209
	s_or_b64 exec, exec, s[12:13]
	s_waitcnt lgkmcnt(0)
	v_add_u32_e32 v27, v194, v193
	ds_read_b128 v[218:221], v27
	ds_read_b128 v[222:225], v27 offset:32
	s_waitcnt lgkmcnt(0)
	v_pk_mul_f32 v[32:33], v[32:33], v[218:219]
	v_pk_mul_f32 v[34:35], v[34:35], v[220:221]
	v_pk_mul_f32 v[36:37], v[36:37], v[222:223]
	v_pk_mul_f32 v[38:39], v[38:39], v[224:225]
	v_pk_mul_f32 v[48:49], v[48:49], v[218:219]
	v_pk_mul_f32 v[50:51], v[50:51], v[220:221]
	v_pk_mul_f32 v[52:53], v[52:53], v[222:223]
	v_pk_mul_f32 v[54:55], v[54:55], v[224:225]
	v_pk_mul_f32 v[64:65], v[64:65], v[218:219]
	v_pk_mul_f32 v[66:67], v[66:67], v[220:221]
	v_pk_mul_f32 v[68:69], v[68:69], v[222:223]
	v_pk_mul_f32 v[70:71], v[70:71], v[224:225]
	v_pk_mul_f32 v[0:1], v[0:1], v[218:219]
	v_pk_mul_f32 v[2:3], v[2:3], v[220:221]
	v_pk_mul_f32 v[4:5], v[4:5], v[222:223]
	v_pk_mul_f32 v[6:7], v[6:7], v[224:225]
	ds_read_b128 v[218:221], v27 offset:64
	ds_read_b128 v[222:225], v27 offset:96
	s_waitcnt lgkmcnt(0)
	v_pk_mul_f32 v[40:41], v[40:41], v[218:219]
	v_pk_mul_f32 v[42:43], v[42:43], v[220:221]
	v_pk_mul_f32 v[44:45], v[44:45], v[222:223]
	v_pk_mul_f32 v[46:47], v[46:47], v[224:225]
	v_pk_mul_f32 v[56:57], v[56:57], v[218:219]
	v_pk_mul_f32 v[58:59], v[58:59], v[220:221]
	v_pk_mul_f32 v[60:61], v[60:61], v[222:223]
	v_pk_mul_f32 v[62:63], v[62:63], v[224:225]
	v_pk_mul_f32 v[72:73], v[72:73], v[218:219]
	v_pk_mul_f32 v[74:75], v[74:75], v[220:221]
	v_pk_mul_f32 v[76:77], v[76:77], v[222:223]
	v_pk_mul_f32 v[78:79], v[78:79], v[224:225]
	v_pk_mul_f32 v[8:9], v[8:9], v[218:219]
	v_pk_mul_f32 v[10:11], v[10:11], v[220:221]
	v_pk_mul_f32 v[12:13], v[12:13], v[222:223]
	v_pk_mul_f32 v[14:15], v[14:15], v[224:225]
	v_mov_b32_e32 v209, 1.0
	s_branch .Latt_rescA_cont
.Latt_resc_B:
	s_and_saveexec_b64 s[12:13], s[10:11]
	ds_write_b32 v195, v26
	s_or_b64 exec, exec, s[12:13]
	s_waitcnt lgkmcnt(0)
	v_add_u32_e32 v27, v194, v193
	ds_read_b128 v[234:237], v27
	ds_read_b128 v[238:241], v27 offset:32
	s_waitcnt lgkmcnt(0)
	v_pk_mul_f32 v[32:33], v[32:33], v[234:235]
	v_pk_mul_f32 v[34:35], v[34:35], v[236:237]
	v_pk_mul_f32 v[36:37], v[36:37], v[238:239]
	v_pk_mul_f32 v[38:39], v[38:39], v[240:241]
	v_pk_mul_f32 v[48:49], v[48:49], v[234:235]
	v_pk_mul_f32 v[50:51], v[50:51], v[236:237]
	v_pk_mul_f32 v[52:53], v[52:53], v[238:239]
	v_pk_mul_f32 v[54:55], v[54:55], v[240:241]
	v_pk_mul_f32 v[64:65], v[64:65], v[234:235]
	v_pk_mul_f32 v[66:67], v[66:67], v[236:237]
	v_pk_mul_f32 v[68:69], v[68:69], v[238:239]
	v_pk_mul_f32 v[70:71], v[70:71], v[240:241]
	v_pk_mul_f32 v[0:1], v[0:1], v[234:235]
	v_pk_mul_f32 v[2:3], v[2:3], v[236:237]
	v_pk_mul_f32 v[4:5], v[4:5], v[238:239]
	v_pk_mul_f32 v[6:7], v[6:7], v[240:241]
	ds_read_b128 v[234:237], v27 offset:64
	ds_read_b128 v[238:241], v27 offset:96
	s_waitcnt lgkmcnt(0)
	v_pk_mul_f32 v[40:41], v[40:41], v[234:235]
	v_pk_mul_f32 v[42:43], v[42:43], v[236:237]
	v_pk_mul_f32 v[44:45], v[44:45], v[238:239]
	v_pk_mul_f32 v[46:47], v[46:47], v[240:241]
	v_pk_mul_f32 v[56:57], v[56:57], v[234:235]
	v_pk_mul_f32 v[58:59], v[58:59], v[236:237]
	v_pk_mul_f32 v[60:61], v[60:61], v[238:239]
	v_pk_mul_f32 v[62:63], v[62:63], v[240:241]
	v_pk_mul_f32 v[72:73], v[72:73], v[234:235]
	v_pk_mul_f32 v[74:75], v[74:75], v[236:237]
	v_pk_mul_f32 v[76:77], v[76:77], v[238:239]
	v_pk_mul_f32 v[78:79], v[78:79], v[240:241]
	v_pk_mul_f32 v[8:9], v[8:9], v[234:235]
	v_pk_mul_f32 v[10:11], v[10:11], v[236:237]
	v_pk_mul_f32 v[12:13], v[12:13], v[238:239]
	v_pk_mul_f32 v[14:15], v[14:15], v[240:241]
	v_mov_b32_e32 v26, 1.0
	s_branch .Latt_rescB_cont

	.amdhsa_kernel _Z8mega_fwd4Args
		.amdhsa_group_segment_fixed_size 0
		.amdhsa_private_segment_fixed_size 0
		.amdhsa_kernarg_size 464
		.amdhsa_user_sgpr_count 2
		.amdhsa_user_sgpr_dispatch_ptr 0
		.amdhsa_user_sgpr_queue_ptr 0
		.amdhsa_user_sgpr_kernarg_segment_ptr 1
		.amdhsa_user_sgpr_dispatch_id 0
		.amdhsa_user_sgpr_kernarg_preload_length 0
		.amdhsa_user_sgpr_kernarg_preload_offset 0
		.amdhsa_user_sgpr_private_segment_size 0
		.amdhsa_uses_dynamic_stack 0
		.amdhsa_enable_private_segment 0
		.amdhsa_system_sgpr_workgroup_id_x 1
		.amdhsa_system_sgpr_workgroup_id_y 0
		.amdhsa_system_sgpr_workgroup_id_z 0
		.amdhsa_system_sgpr_workgroup_info 0
		.amdhsa_system_vgpr_workitem_id 2
		.amdhsa_next_free_vgpr 251
		.amdhsa_next_free_sgpr 102
		.amdhsa_accum_offset 252
		.amdhsa_reserve_vcc 1
		.amdhsa_float_round_mode_32 0
		.amdhsa_float_round_mode_16_64 0
		.amdhsa_float_denorm_mode_32 3
		.amdhsa_float_denorm_mode_16_64 3
		.amdhsa_dx10_clamp 1
		.amdhsa_ieee_mode 1
		.amdhsa_fp16_overflow 0
		.amdhsa_tg_split 0
		.amdhsa_exception_fp_ieee_invalid_op 0
		.amdhsa_exception_fp_denorm_src 0
		.amdhsa_exception_fp_ieee_div_zero 0
		.amdhsa_exception_fp_ieee_overflow 0
		.amdhsa_exception_fp_ieee_underflow 0
		.amdhsa_exception_fp_ieee_inexact 0
		.amdhsa_exception_int_div_zero 0
	.end_amdhsa_kernel

amdhsa.kernels:
  - .agpr_count:     0
    .args:
      - .offset:         0
        .size:           208
        .value_kind:     by_value
      - .offset:         208
        .size:           4
        .value_kind:     hidden_block_count_x
      - .offset:         212
        .size:           4
        .value_kind:     hidden_block_count_y
      - .offset:         216
        .size:           4
        .value_kind:     hidden_block_count_z
      - .offset:         220
        .size:           2
        .value_kind:     hidden_group_size_x
      - .offset:         222
        .size:           2
        .value_kind:     hidden_group_size_y
      - .offset:         224
        .size:           2
        .value_kind:     hidden_group_size_z
      - .offset:         226
        .size:           2
        .value_kind:     hidden_remainder_x
      - .offset:         228
        .size:           2
        .value_kind:     hidden_remainder_y
      - .offset:         230
        .size:           2
        .value_kind:     hidden_remainder_z
      - .offset:         248
        .size:           8
        .value_kind:     hidden_global_offset_x
      - .offset:         256
        .size:           8
        .value_kind:     hidden_global_offset_y
      - .offset:         264
        .size:           8
        .value_kind:     hidden_global_offset_z
      - .offset:         272
        .size:           2
        .value_kind:     hidden_grid_dims
      - .offset:         296
        .size:           8
        .value_kind:     hidden_multigrid_sync_arg
      - .offset:         328
        .size:           4
        .value_kind:     hidden_dynamic_lds_size
    .group_segment_fixed_size: 0
    .kernarg_segment_align: 8
    .kernarg_segment_size: 464
    .language:       OpenCL C
    .language_version:
      - 2
      - 0
    .max_flat_workgroup_size: 512
    .name:           _Z8mega_fwd4Args
    .private_segment_fixed_size: 0
    .sgpr_count:     108
    .sgpr_spill_count: 65
    .symbol:         _Z8mega_fwd4Args.kd
    .uniform_work_group_size: 1
    .uses_dynamic_stack: false
    .vgpr_count:     251
    .vgpr_spill_count: 0
    .wavefront_size: 64
